# grid barrier cross-XCD step: per-XCD write-through flag slots polled by all leaders (no TOP atomic, no TOPGEN hop)
# baseline (speedup 1.0000x reference)
.LBB0_1128:
	s_andn2_saveexec_b64 s[8:9], s[8:9]
	s_cbranch_execz .LBB0_1148
	s_mov_b64 s[8:9], exec
	buffer_wbl2 sc1
	s_waitcnt lgkmcnt(0)
	s_waitcnt vmcnt(0)
	buffer_inv sc1
	v_readfirstlane_b32 s22, v7
	v_readfirstlane_b32 s28, v2
	v_readlane_b32 s10, v253, 30
	v_readlane_b32 s11, v253, 31
	v_readlane_b32 s20, v253, 26
	s_sub_u32 s21, s20, s10
	s_add_u32 s21, s21, 0x2000
	s_lshr_b32 s21, s21, 6
	s_add_u32 s10, s10, 0x8000
	s_addc_u32 s11, s11, 0
	v_mov_b32_e32 v4, s22
	v_mov_b32_e32 v5, s21
	s_nop 1
	global_store_dword v5, v4, s[10:11] sc1
	s_mov_b64 s[26:27], exec
	s_mov_b64 exec, 0xff
	v_mbcnt_lo_u32_b32 v6, -1, 0
	v_lshlrev_b32_e32 v6, 2, v6
.Lxt_poll:
	global_load_dword v5, v6, s[10:11] sc1
	s_waitcnt vmcnt(0)
	v_cmp_le_u32_e32 vcc, s22, v5
	s_nop 1
	s_bcnt1_i32_b64 s29, vcc
	s_cmp_ge_u32 s29, s28
	s_cbranch_scc1 .Lxt_all
	s_sleep 1
	s_branch .Lxt_poll
.Lxt_all:
	s_mov_b64 exec, s[26:27]
	s_mov_b64 s[8:9], exec
